# MLA: next-tile LDS-DMA issue interleaved into the QK^T MFMA stream
# baseline (speedup 1.0000x reference)
; #define LAS __attribute__((address_space(3)))
; #define SBAR() __builtin_amdgcn_sched_barrier(0)
; template <int TYPE>
; __device__ __forceinline__ void attn_item(const Params& p, int layer, int head, int qb, int mode, LAS unsigned char* lds) {
;     ...
;     float m_reg = -1e30f, l_reg = 0.f; f32x16 o[4];
; #pragma unroll
;     for (int d = 0; d < 4; ++d) o[d] = (f32x16){};
;     constexpr int T0 = PADR / 64;
;     int tbeg = T0; float Bb = 0.f;
;     if (TYPE == 1) {
;         const float* gq = p.in[I_GFQ] + layer * 128; const float* gk = p.in[I_GFK] + layer * 128;
;         float gm = fmaxf(fabsf(gq[lane] * gk[lane]), fabsf(gq[lane + 64] * gk[lane + 64]));
; #pragma unroll
;         for (int o_ = 32; o_ >= 1; o_ >>= 1) gm = fmaxf(gm, __shfl_xor(gm, o_));
;         Bb = gm * 11.313708498984761f * LOG2E * 1.02f;
;     }
;     int tend = NT;
;     if (TYPE == 0 && mode != 0) { const int mid = (T0 + NT + 1) >> 1; if (mode == 1) tend = mid; else tbeg = mid; }
;     const int ntiles = tend - tbeg, tfirst = TYPE == 1 ? tend - 1 : tbeg;
;     LAS float* xm = (LAS float*)(lds + LDS_BYTES - 2048);
;     ADMA(tfirst, tfirst & 1);
;     asm volatile("s_waitcnt vmcnt(0)" ::: "memory");
;     __syncthreads();
;     int kb[4], kbr[4];
; #pragma unroll
;     for (int dd = 0; dd < 4; ++dd) { kb[dd] = r32 * 256 + ((((dd * 2 + hi) ^ (r32 & 7))) << 4); kbr[dd] = 16384 + r32 * 128 + ((((dd * 2 + hi) ^ (r32 & 7))) << 4); }
;     for (int it2 = 0; it2 < ntiles; ++it2) {
;         const int t = TYPE == 1 ? tfirst - it2 : tfirst + it2, tn = TYPE == 1 ? t - 1 : t + 1;
;         const int bf = t & 1, kbase = t * 64;
;         if (it2 + 1 < ntiles) { ADMA(tn, bf ^ 1); }
;         if (kbase <= w_last) {
;             f32x16 p0 = (f32x16){}, p1 = (f32x16){};
;             const LAS unsigned char* kt = K_lds + bf * SHM_K;
; #pragma unroll
;             for (int d0 = 0; d0 < NQ; ++d0) {
;                 const LAS unsigned char* a = d0 < 8 ? kt + kb[d0 & 3] + (d0 >> 2) * 128 : kt + kbr[d0 & 3];
;                 const bf16x8 b0 = *(const LAS bf16x8*)a, b1 = *(const LAS bf16x8*)(a + (d0 < 8 ? 32 * 256 : 32 * 128));
;                 p0 = __builtin_amdgcn_mfma_f32_32x32x16_bf16(b0, qr[d0], p0, 0, 0, 0);
;                 p1 = __builtin_amdgcn_mfma_f32_32x32x16_bf16(b1, qr[d0], p1, 0, 0, 0);
;                 if ((d0 & 3) == 3) SBAR();
.LBB0_819:
	s_add_i32 s18, s14, s12
	s_and_b32 s28, s18, 1
	s_add_i32 s12, s12, 1
	s_cmp_ge_i32 s12, s7
	s_cselect_b64 s[38:39], -1, 0
	s_cmp_gt_i32 s11, s10
	s_cbranch_scc1 .Lq_skip
	s_mul_i32 s19, s28, 0x6000
	s_add_i32 s19, s19, 0
	s_and_b64 vcc, exec, s[38:39]
	s_cbranch_vccnz .Lq_plain
	v_add_u32_e32 v102, s19, v230
	v_add_u32_e32 v103, v102, v228
	v_add_u32_e32 v104, s19, v231
	v_add_u32_e32 v105, v104, v228
	v_add_u32_e32 v106, s19, v232
	v_add_u32_e32 v107, v106, v228
	v_add_u32_e32 v108, s19, v233
	v_add_u32_e32 v109, v108, v228
	v_add_u32_e32 v248, v102, v229
	v_add_u32_e32 v249, v104, v229
	v_add_u32_e32 v250, v106, v229
	v_add_u32_e32 v251, v108, v229
	ds_read_b128 v[98:101], v103 offset:32768
	ds_read_b128 v[110:113], v103 offset:40960
	ds_read_b128 v[114:117], v105 offset:32768
	ds_read_b128 v[118:121], v105 offset:40960
	ds_read_b128 v[122:125], v107 offset:32768
	ds_read_b128 v[126:129], v107 offset:40960
	ds_read_b128 v[178:181], v109 offset:32768
	ds_read_b128 v[182:185], v109 offset:40960
	ds_read_b128 v[186:189], v103 offset:32896
	ds_read_b128 v[190:193], v103 offset:41088
	ds_read_b128 v[240:243], v105 offset:32896
	ds_read_b128 v[244:247], v105 offset:41088
	s_waitcnt lgkmcnt(11)
	v_mfma_f32_32x32x16_bf16 v[82:97], v[98:101], v[130:133], 0
	ds_read_b128 v[98:101], v107 offset:32896
	s_waitcnt lgkmcnt(11)
	v_mfma_f32_32x32x16_bf16 v[66:81], v[110:113], v[130:133], 0
	ds_read_b128 v[110:113], v107 offset:41088
	s_xor_b32 s19, s28, 1
	s_mul_i32 s29, s19, 0x6000
	s_lshl_b32 s19, s19, 13
	s_add_i32 s29, s29, s6
	s_sub_i32 s19, s29, s19
	v_lshl_add_u64 v[194:195], s[34:35], 0, v[208:209]
	s_add_i32 m0, s29, 0x8000
	s_nop 0
	global_load_lds_dwordx4 v[194:195], off
	s_waitcnt lgkmcnt(11)
	v_mfma_f32_32x32x16_bf16 v[82:97], v[114:117], v[134:137], v[82:97]
	ds_read_b128 v[114:117], v109 offset:32896
	s_waitcnt lgkmcnt(11)
	v_mfma_f32_32x32x16_bf16 v[66:81], v[118:121], v[134:137], v[66:81]
	ds_read_b128 v[118:121], v109 offset:41088
	v_lshl_add_u64 v[196:197], s[34:35], 0, v[204:205]
	s_mov_b32 m0, s19
	s_nop 0
	global_load_lds_dwordx4 v[196:197], off
	s_waitcnt lgkmcnt(11)
	v_mfma_f32_32x32x16_bf16 v[82:97], v[122:125], v[138:141], v[82:97]
	ds_read_b128 v[122:125], v248 offset:49152
	s_waitcnt lgkmcnt(11)
	v_mfma_f32_32x32x16_bf16 v[66:81], v[126:129], v[138:141], v[66:81]
	ds_read_b128 v[126:129], v248 offset:53248
	v_lshl_add_u64 v[194:195], s[34:35], 0, v[206:207]
	s_add_i32 m0, s29, 0xa000
	s_nop 0
	global_load_lds_dwordx4 v[194:195], off
	s_waitcnt lgkmcnt(11)
	v_mfma_f32_32x32x16_bf16 v[82:97], v[178:181], v[142:145], v[82:97]
	ds_read_b128 v[178:181], v249 offset:49152
	s_waitcnt lgkmcnt(11)
	v_mfma_f32_32x32x16_bf16 v[66:81], v[182:185], v[142:145], v[66:81]
	ds_read_b128 v[182:185], v249 offset:53248
	v_lshl_add_u64 v[196:197], s[34:35], 0, v[202:203]
	s_add_i32 m0, s19, 0x2000
	s_nop 0
	global_load_lds_dwordx4 v[196:197], off
	s_waitcnt lgkmcnt(11)
	v_mfma_f32_32x32x16_bf16 v[82:97], v[186:189], v[146:149], v[82:97]
	ds_read_b128 v[186:189], v250 offset:49152
	s_waitcnt lgkmcnt(11)
	v_mfma_f32_32x32x16_bf16 v[66:81], v[190:193], v[146:149], v[66:81]
	ds_read_b128 v[190:193], v250 offset:53248
	v_lshl_add_u64 v[194:195], s[34:35], 0, v[200:201]
	s_add_i32 m0, s29, 0xc000
	s_nop 0
	global_load_lds_dwordx4 v[194:195], off
	s_waitcnt lgkmcnt(11)
	v_mfma_f32_32x32x16_bf16 v[82:97], v[240:243], v[150:153], v[82:97]
	ds_read_b128 v[240:243], v251 offset:49152
	s_waitcnt lgkmcnt(11)
	v_mfma_f32_32x32x16_bf16 v[66:81], v[244:247], v[150:153], v[66:81]
	ds_read_b128 v[244:247], v251 offset:53248
	s_waitcnt lgkmcnt(11)
	v_mfma_f32_32x32x16_bf16 v[82:97], v[98:101], v[154:157], v[82:97]
	s_waitcnt lgkmcnt(10)
	v_mfma_f32_32x32x16_bf16 v[66:81], v[110:113], v[154:157], v[66:81]
	s_waitcnt lgkmcnt(9)
	v_mfma_f32_32x32x16_bf16 v[82:97], v[114:117], v[158:161], v[82:97]
	s_waitcnt lgkmcnt(8)
	v_mfma_f32_32x32x16_bf16 v[66:81], v[118:121], v[158:161], v[66:81]
	s_waitcnt lgkmcnt(7)
	v_mfma_f32_32x32x16_bf16 v[82:97], v[122:125], v[162:165], v[82:97]
	s_waitcnt lgkmcnt(6)
	v_mfma_f32_32x32x16_bf16 v[66:81], v[126:129], v[162:165], v[66:81]
	s_waitcnt lgkmcnt(5)
	v_mfma_f32_32x32x16_bf16 v[82:97], v[178:181], v[166:169], v[82:97]
	s_waitcnt lgkmcnt(4)
	v_mfma_f32_32x32x16_bf16 v[66:81], v[182:185], v[166:169], v[66:81]
	s_waitcnt lgkmcnt(3)
	v_mfma_f32_32x32x16_bf16 v[82:97], v[186:189], v[170:173], v[82:97]
	s_waitcnt lgkmcnt(2)
	v_mfma_f32_32x32x16_bf16 v[66:81], v[190:193], v[170:173], v[66:81]
	s_waitcnt lgkmcnt(1)
	v_mfma_f32_32x32x16_bf16 v[82:97], v[240:243], v[174:177], v[82:97]
	s_waitcnt lgkmcnt(0)
	v_mfma_f32_32x32x16_bf16 v[66:81], v[244:247], v[174:177], v[66:81]
	s_branch .Lq_sm
.Lq_skip:
	s_and_b64 vcc, exec, s[38:39]
	s_cbranch_vccnz .LBB0_818
	s_xor_b32 s19, s28, 1
	s_mul_i32 s29, s19, 0x6000
	s_add_i32 s29, s29, 0
	s_lshl_b32 s19, s19, 13
	s_add_i32 s29, s29, s6
	v_lshl_add_u64 v[66:67], s[34:35], 0, v[208:209]
	s_add_i32 m0, s29, 0x8000
	s_sub_i32 s19, s29, s19
	global_load_lds_dwordx4 v[66:67], off
	v_lshl_add_u64 v[66:67], s[34:35], 0, v[204:205]
	s_mov_b32 m0, s19
	s_nop 0
	global_load_lds_dwordx4 v[66:67], off
	v_lshl_add_u64 v[66:67], s[34:35], 0, v[206:207]
	s_add_i32 m0, s29, 0xa000
	s_nop 0
	global_load_lds_dwordx4 v[66:67], off
	v_lshl_add_u64 v[66:67], s[34:35], 0, v[202:203]
	s_add_i32 m0, s19, 0x2000
	s_nop 0
	global_load_lds_dwordx4 v[66:67], off
	v_lshl_add_u64 v[66:67], s[34:35], 0, v[200:201]
	s_add_i32 m0, s29, 0xc000
	s_nop 0
	global_load_lds_dwordx4 v[66:67], off
	s_branch .LBB0_818
; #define LAS __attribute__((address_space(3)))
; template <int TYPE>
; __device__ __forceinline__ void attn_item(const Params& p, int layer, int head, int qb, int mode, LAS unsigned char* lds) {
;     ...
;         if (kbase <= w_last) {
;             f32x16 p0 = (f32x16){}, p1 = (f32x16){};
;             const LAS unsigned char* kt = K_lds + bf * SHM_K;
; #pragma unroll
;             for (int d0 = 0; d0 < NQ; ++d0) {
;                 const LAS unsigned char* a = d0 < 8 ? kt + kb[d0 & 3] + (d0 >> 2) * 128 : kt + kbr[d0 & 3];
;                 const bf16x8 b0 = *(const LAS bf16x8*)a, b1 = *(const LAS bf16x8*)(a + (d0 < 8 ? 32 * 256 : 32 * 128));
;                 p0 = __builtin_amdgcn_mfma_f32_32x32x16_bf16(b0, qr[d0], p0, 0, 0, 0);
;                 p1 = __builtin_amdgcn_mfma_f32_32x32x16_bf16(b1, qr[d0], p1, 0, 0, 0);
;                 if ((d0 & 3) == 3) SBAR();
;             }
;             if (TYPE == 1) {
;                 const LAS float* bb = B_lds + bf * 64 + 4 * hi;
; #pragma unroll
;                 for (int q4 = 0; q4 < 4; ++q4) {
;                     const f32x4 b0 = *(const LAS f32x4*)(bb + 8 * q4), b1 = *(const LAS f32x4*)(bb + 32 + 8 * q4);
; #pragma unroll
;                     for (int j = 0; j < 4; ++j) { p0[q4 * 4 + j] += b0[j]; p1[q4 * 4 + j] += b1[j]; }
;                 }
;             }
;             if (TYPE == 1 && kbase + 63 > w_first) {
;                 const int lim = my_kmax - kbase - 4 * hi; const float NEGI = -__builtin_inff();
; #pragma unroll
;                 for (int r = 0; r < 16; ++r) { const int c = (r & 3) + 8 * (r >> 2); if (c > lim) p0[r] = NEGI; if (c + 32 > lim) p1[r] = NEGI; }
;             }
;             if (t == T0) {
;                 const int lo = (PADR & 63) - 4 * hi; const float NEGI = -__builtin_inff();
; #pragma unroll
;                 for (int r = 0; r < 16; ++r) { const int c = (r & 3) + 8 * (r >> 2); if (c < lo) p0[r] = NEGI; if (c + 32 < lo) p1[r] = NEGI; }
;             }
;             float pmax = p0[0];
; #pragma unroll
;             for (int r = 1; r < 16; ++r) pmax = fmaxf(pmax, p0[r]);
; #pragma unroll
;             for (int r = 0; r < 16; ++r) pmax = fmaxf(pmax, p1[r]);
;             { auto rr = __builtin_amdgcn_permlane32_swap(__float_as_uint(pmax), __float_as_uint(pmax), false, false);
;               pmax = fmaxf(__uint_as_float(rr[0]), __uint_as_float(rr[1])); }
;             float mn, alpha;
.Lq_plain:
	v_add_u32_e32 v102, s19, v230
	v_add_u32_e32 v103, v102, v228
	v_add_u32_e32 v104, s19, v231
	v_add_u32_e32 v105, v104, v228
	v_add_u32_e32 v106, s19, v232
	v_add_u32_e32 v107, v106, v228
	v_add_u32_e32 v108, s19, v233
	v_add_u32_e32 v109, v108, v228
	v_add_u32_e32 v248, v102, v229
	v_add_u32_e32 v249, v104, v229
	v_add_u32_e32 v250, v106, v229
	v_add_u32_e32 v251, v108, v229
	ds_read_b128 v[98:101], v103 offset:32768
	ds_read_b128 v[110:113], v103 offset:40960
	ds_read_b128 v[114:117], v105 offset:32768
	ds_read_b128 v[118:121], v105 offset:40960
	ds_read_b128 v[122:125], v107 offset:32768
	ds_read_b128 v[126:129], v107 offset:40960
	ds_read_b128 v[178:181], v109 offset:32768
	ds_read_b128 v[182:185], v109 offset:40960
	ds_read_b128 v[186:189], v103 offset:32896
	ds_read_b128 v[190:193], v103 offset:41088
	ds_read_b128 v[240:243], v105 offset:32896
	ds_read_b128 v[244:247], v105 offset:41088
	s_waitcnt lgkmcnt(11)
	v_mfma_f32_32x32x16_bf16 v[82:97], v[98:101], v[130:133], 0
	ds_read_b128 v[98:101], v107 offset:32896
	s_waitcnt lgkmcnt(11)
	v_mfma_f32_32x32x16_bf16 v[66:81], v[110:113], v[130:133], 0
	ds_read_b128 v[110:113], v107 offset:41088
	s_waitcnt lgkmcnt(11)
	v_mfma_f32_32x32x16_bf16 v[82:97], v[114:117], v[134:137], v[82:97]
	ds_read_b128 v[114:117], v109 offset:32896
	s_waitcnt lgkmcnt(11)
	v_mfma_f32_32x32x16_bf16 v[66:81], v[118:121], v[134:137], v[66:81]
	ds_read_b128 v[118:121], v109 offset:41088
	s_waitcnt lgkmcnt(11)
	v_mfma_f32_32x32x16_bf16 v[82:97], v[122:125], v[138:141], v[82:97]
	ds_read_b128 v[122:125], v248 offset:49152
	s_waitcnt lgkmcnt(11)
	v_mfma_f32_32x32x16_bf16 v[66:81], v[126:129], v[138:141], v[66:81]
	ds_read_b128 v[126:129], v248 offset:53248
	s_waitcnt lgkmcnt(11)
	v_mfma_f32_32x32x16_bf16 v[82:97], v[178:181], v[142:145], v[82:97]
	ds_read_b128 v[178:181], v249 offset:49152
	s_waitcnt lgkmcnt(11)
	v_mfma_f32_32x32x16_bf16 v[66:81], v[182:185], v[142:145], v[66:81]
	ds_read_b128 v[182:185], v249 offset:53248
	s_waitcnt lgkmcnt(11)
	v_mfma_f32_32x32x16_bf16 v[82:97], v[186:189], v[146:149], v[82:97]
	ds_read_b128 v[186:189], v250 offset:49152
	s_waitcnt lgkmcnt(11)
	v_mfma_f32_32x32x16_bf16 v[66:81], v[190:193], v[146:149], v[66:81]
	ds_read_b128 v[190:193], v250 offset:53248
	s_waitcnt lgkmcnt(11)
	v_mfma_f32_32x32x16_bf16 v[82:97], v[240:243], v[150:153], v[82:97]
	ds_read_b128 v[240:243], v251 offset:49152
	s_waitcnt lgkmcnt(11)
	v_mfma_f32_32x32x16_bf16 v[66:81], v[244:247], v[150:153], v[66:81]
	ds_read_b128 v[244:247], v251 offset:53248
	s_waitcnt lgkmcnt(11)
	v_mfma_f32_32x32x16_bf16 v[82:97], v[98:101], v[154:157], v[82:97]
	s_waitcnt lgkmcnt(10)
	v_mfma_f32_32x32x16_bf16 v[66:81], v[110:113], v[154:157], v[66:81]
	s_waitcnt lgkmcnt(9)
	v_mfma_f32_32x32x16_bf16 v[82:97], v[114:117], v[158:161], v[82:97]
	s_waitcnt lgkmcnt(8)
	v_mfma_f32_32x32x16_bf16 v[66:81], v[118:121], v[158:161], v[66:81]
	s_waitcnt lgkmcnt(7)
	v_mfma_f32_32x32x16_bf16 v[82:97], v[122:125], v[162:165], v[82:97]
	s_waitcnt lgkmcnt(6)
	v_mfma_f32_32x32x16_bf16 v[66:81], v[126:129], v[162:165], v[66:81]
	s_waitcnt lgkmcnt(5)
	v_mfma_f32_32x32x16_bf16 v[82:97], v[178:181], v[166:169], v[82:97]
	s_waitcnt lgkmcnt(4)
	v_mfma_f32_32x32x16_bf16 v[66:81], v[182:185], v[166:169], v[66:81]
	s_waitcnt lgkmcnt(3)
	v_mfma_f32_32x32x16_bf16 v[82:97], v[186:189], v[170:173], v[82:97]
	s_waitcnt lgkmcnt(2)
	v_mfma_f32_32x32x16_bf16 v[66:81], v[190:193], v[170:173], v[66:81]
	s_waitcnt lgkmcnt(1)
	v_mfma_f32_32x32x16_bf16 v[82:97], v[240:243], v[174:177], v[82:97]
	s_waitcnt lgkmcnt(0)
	v_mfma_f32_32x32x16_bf16 v[66:81], v[244:247], v[174:177], v[66:81]
.Lq_sm:
	s_cmp_eq_u32 s18, 3
	s_cselect_b64 vcc, -1, 0
	s_nop 7
	v_cndmask_b32_e32 v82, v82, v219, vcc
	v_cndmask_b32_e32 v83, v83, v219, vcc
	v_max_f32_e32 v98, v83, v83
	v_max_f32_e32 v99, v82, v82
	v_cndmask_b32_e32 v85, v85, v219, vcc
	v_cndmask_b32_e32 v84, v84, v219, vcc
	v_max_f32_e32 v98, v99, v98
	v_cndmask_b32_e32 v87, v87, v219, vcc
	v_cndmask_b32_e32 v86, v86, v219, vcc
	v_max3_f32 v98, v98, v84, v85
	v_cndmask_b32_e32 v89, v89, v219, vcc
	v_cndmask_b32_e32 v88, v88, v219, vcc
	v_max3_f32 v98, v98, v86, v87
	v_cndmask_b32_e32 v91, v91, v219, vcc
	v_cndmask_b32_e32 v90, v90, v219, vcc
	v_max3_f32 v98, v98, v88, v89
	v_cndmask_b32_e32 v93, v93, v219, vcc
	v_cndmask_b32_e32 v92, v92, v219, vcc
	v_max3_f32 v98, v98, v90, v91
	v_cndmask_b32_e32 v95, v95, v219, vcc
	v_cndmask_b32_e32 v94, v94, v219, vcc
	v_max3_f32 v98, v98, v92, v93
	v_cndmask_b32_e32 v97, v97, v219, vcc
	v_cndmask_b32_e32 v96, v96, v219, vcc
	v_max3_f32 v98, v98, v94, v95
	v_cndmask_b32_e32 v67, v67, v219, vcc
	v_cndmask_b32_e32 v66, v66, v219, vcc
	v_max3_f32 v98, v98, v96, v97
	v_cndmask_b32_e32 v69, v69, v219, vcc
	v_cndmask_b32_e32 v68, v68, v219, vcc
	v_max3_f32 v98, v98, v66, v67
	v_cndmask_b32_e32 v71, v71, v219, vcc
	v_cndmask_b32_e32 v70, v70, v219, vcc
	v_max3_f32 v98, v98, v68, v69
	v_cndmask_b32_e32 v73, v73, v219, vcc
	v_cndmask_b32_e32 v72, v72, v219, vcc
	v_max3_f32 v98, v98, v70, v71
	v_max3_f32 v98, v98, v72, v73
	v_max3_f32 v98, v98, v74, v75
	v_max3_f32 v98, v98, v76, v77
	v_max3_f32 v98, v98, v78, v79
	v_max3_f32 v98, v98, v80, v81
	v_mov_b32_e32 v99, v98
	s_nop 1
	v_permlane32_swap_b32_e32 v98, v99
	v_max_f32_e32 v99, v99, v99
	v_max_f32_e32 v98, v98, v98
	v_max_f32_e32 v98, v98, v99
	v_sub_f32_e32 v99, v98, v198
	s_mov_b32 s18, 0x41380000
	v_cmp_ge_f32_e32 vcc, s18, v99
	s_cmp_eq_u64 vcc, exec
	v_max_f32_e32 v99, v198, v198
; __device__ __forceinline__ int crow(int r, int hi) { return (r & 3) + 8 * (r >> 2) + 4 * hi; }
; template <int TYPE>
; __device__ __forceinline__ void attn_item(const Params& p, int layer, int head, int qb, int mode, LAS unsigned char* lds) {
;     ...
;             float mn, alpha;
;             if (__all((pmax - m_reg) <= (TYPE == 1 ? 2.0f : 11.5f))) { mn = m_reg; alpha = 1.f; }
;             else { mn = fmaxf(m_reg, pmax); alpha = __builtin_amdgcn_exp2f(m_reg - mn); m_reg = mn; }
;             float ps = 0.f;
; #pragma unroll
;             for (int r = 0; r < 16; ++r) { p0[r] = __builtin_amdgcn_exp2f(p0[r] - mn); p1[r] = __builtin_amdgcn_exp2f(p1[r] - mn); ps += p0[r] + p1[r]; }
;             { auto rr = __builtin_amdgcn_permlane32_swap(__float_as_uint(ps), __float_as_uint(ps), false, false);
;               ps = __uint_as_float(rr[0]) + __uint_as_float(rr[1]); }
;             l_reg = l_reg * alpha + ps;
;             bf16x8 pa0, pa1, pa2, pa3;
;     ...
;             PK4(p0, 0, pa0); PK4(p0, 8, pa1); PK4(p1, 0, pa2); PK4(p1, 8, pa3);
;     ...
;             if (__any(alpha < 1.f)) {
;                 if (hi == 0) wsl[r32] = alpha;
;                 asm volatile("s_waitcnt lgkmcnt(0)" ::: "memory");
; #pragma unroll
;                 for (int r = 0; r < 16; ++r) { const float al = wsl[crow(r, hi)];
; #pragma unroll
;                     for (int d = 0; d < 4; ++d) o[d][r] *= al; }
;             }
	v_max_f32_e32 v98, v99, v98
	s_cselect_b64 vcc, -1, 0
	v_sub_f32_e32 v99, v198, v98
	v_cndmask_b32_e32 v198, v98, v198, vcc
	v_sub_f32_e32 v82, v82, v198
	v_sub_f32_e32 v66, v66, v198
	v_exp_f32_e32 v82, v82
	v_exp_f32_e32 v66, v66
	v_sub_f32_e32 v83, v83, v198
	v_sub_f32_e32 v67, v67, v198
	v_exp_f32_e32 v83, v83
	v_exp_f32_e32 v67, v67
	v_sub_f32_e32 v84, v84, v198
	v_sub_f32_e32 v68, v68, v198
	v_exp_f32_e32 v84, v84
	v_exp_f32_e32 v68, v68
	v_sub_f32_e32 v85, v85, v198
	v_sub_f32_e32 v69, v69, v198
	v_exp_f32_e32 v85, v85
	v_exp_f32_e32 v69, v69
	v_sub_f32_e32 v86, v86, v198
	v_sub_f32_e32 v70, v70, v198
	v_exp_f32_e32 v98, v99
	v_add_f32_e32 v99, v66, v82
	v_exp_f32_e32 v86, v86
	v_exp_f32_e32 v70, v70
	v_sub_f32_e32 v87, v87, v198
	v_sub_f32_e32 v71, v71, v198
	v_add_f32_e32 v99, 0, v99
	v_add_f32_e32 v100, v67, v83
	v_exp_f32_e32 v87, v87
	v_exp_f32_e32 v71, v71
	v_sub_f32_e32 v88, v88, v198
	v_sub_f32_e32 v72, v72, v198
	v_add_f32_e32 v99, v100, v99
	v_add_f32_e32 v100, v68, v84
	v_exp_f32_e32 v88, v88
	v_exp_f32_e32 v72, v72
	v_sub_f32_e32 v89, v89, v198
	v_sub_f32_e32 v73, v73, v198
	v_add_f32_e32 v99, v100, v99
	v_add_f32_e32 v100, v69, v85
	v_exp_f32_e32 v89, v89
	v_exp_f32_e32 v73, v73
	v_sub_f32_e32 v90, v90, v198
	v_sub_f32_e32 v74, v74, v198
	v_add_f32_e32 v99, v100, v99
	v_add_f32_e32 v100, v70, v86
	v_exp_f32_e32 v90, v90
	v_exp_f32_e32 v74, v74
	v_sub_f32_e32 v91, v91, v198
	v_sub_f32_e32 v75, v75, v198
	v_add_f32_e32 v99, v100, v99
	v_add_f32_e32 v100, v71, v87
	v_exp_f32_e32 v91, v91
	v_exp_f32_e32 v75, v75
	v_sub_f32_e32 v92, v92, v198
	v_sub_f32_e32 v76, v76, v198
	v_add_f32_e32 v99, v100, v99
	v_add_f32_e32 v100, v72, v88
	v_exp_f32_e32 v92, v92
	v_exp_f32_e32 v76, v76
	v_sub_f32_e32 v93, v93, v198
	v_sub_f32_e32 v77, v77, v198
	v_add_f32_e32 v99, v100, v99
	v_add_f32_e32 v100, v73, v89
	v_exp_f32_e32 v93, v93
	v_exp_f32_e32 v77, v77
	v_sub_f32_e32 v94, v94, v198
	v_sub_f32_e32 v78, v78, v198
	v_add_f32_e32 v99, v100, v99
	v_add_f32_e32 v100, v74, v90
	v_exp_f32_e32 v94, v94
	v_exp_f32_e32 v78, v78
	v_sub_f32_e32 v95, v95, v198
	v_sub_f32_e32 v79, v79, v198
	v_add_f32_e32 v99, v100, v99
	v_add_f32_e32 v100, v75, v91
	v_exp_f32_e32 v95, v95
	v_exp_f32_e32 v79, v79
	v_sub_f32_e32 v96, v96, v198
	v_sub_f32_e32 v80, v80, v198
	v_add_f32_e32 v99, v100, v99
	v_add_f32_e32 v100, v76, v92
	v_exp_f32_e32 v96, v96
	v_exp_f32_e32 v80, v80
	v_sub_f32_e32 v97, v97, v198
	v_sub_f32_e32 v81, v81, v198
	v_add_f32_e32 v99, v100, v99
	v_add_f32_e32 v100, v77, v93
	v_exp_f32_e32 v97, v97
	v_exp_f32_e32 v81, v81
	v_add_f32_e32 v99, v100, v99
	v_add_f32_e32 v100, v78, v94
	v_add_f32_e32 v99, v100, v99
	v_add_f32_e32 v100, v79, v95
	v_add_f32_e32 v99, v100, v99
	v_add_f32_e32 v100, v80, v96
	v_add_f32_e32 v99, v100, v99
	v_add_f32_e32 v100, v81, v97
	v_add_f32_e32 v237, v100, v99
	v_cndmask_b32_e64 v236, v98, 1.0, vcc
	v_mov_b32_e32 v238, v237
	v_cvt_pk_bf16_f32 v178, v82, v83
	v_cvt_pk_bf16_f32 v179, v84, v85
	v_cvt_pk_bf16_f32 v180, v86, v87
	v_cvt_pk_bf16_f32 v181, v88, v89
	v_cvt_pk_bf16_f32 v182, v90, v91
	v_cvt_pk_bf16_f32 v183, v92, v93
	v_cvt_pk_bf16_f32 v184, v94, v95
	v_cvt_pk_bf16_f32 v185, v96, v97
	v_cvt_pk_bf16_f32 v186, v66, v67
	v_cvt_pk_bf16_f32 v187, v68, v69
	v_cvt_pk_bf16_f32 v188, v70, v71
	v_cvt_pk_bf16_f32 v189, v72, v73
	v_cvt_pk_bf16_f32 v190, v74, v75
	v_cvt_pk_bf16_f32 v191, v76, v77
	v_cvt_pk_bf16_f32 v192, v78, v79
	v_cvt_pk_bf16_f32 v193, v80, v81
	s_nop 1
	v_permlane32_swap_b32_e32 v237, v238
	v_permlane32_swap_b32_e32 v178, v180
	v_permlane32_swap_b32_e32 v179, v181
	v_permlane32_swap_b32_e32 v182, v184
	v_permlane32_swap_b32_e32 v183, v185
	v_permlane32_swap_b32_e32 v186, v188
	v_permlane32_swap_b32_e32 v187, v189
	v_permlane32_swap_b32_e32 v190, v192
	v_permlane32_swap_b32_e32 v191, v193
	v_cmp_gt_f32_e32 vcc, 1.0, v236
	s_cbranch_vccz .LBB0_826
	s_and_saveexec_b64 s[40:41], s[0:1]
	ds_write_b32 v235, v236
	s_or_b64 exec, exec, s[40:41]
	s_waitcnt lgkmcnt(0)
	ds_read_b128 v[66:69], v0 offset:96
	ds_read_b128 v[70:73], v0 offset:64
	ds_read_b128 v[74:77], v0 offset:32
	ds_read_b128 v[78:81], v0
	s_waitcnt lgkmcnt(0)
	v_pk_mul_f32 v[14:15], v[14:15], v[66:67]
	v_pk_mul_f32 v[10:11], v[10:11], v[70:71]
	v_pk_mul_f32 v[6:7], v[6:7], v[74:75]
	v_pk_mul_f32 v[16:17], v[16:17], v[68:69]
	v_pk_mul_f32 v[12:13], v[12:13], v[72:73]
	v_pk_mul_f32 v[8:9], v[8:9], v[76:77]
	v_pk_mul_f32 v[4:5], v[4:5], v[80:81]
	v_pk_mul_f32 v[2:3], v[2:3], v[78:79]
	v_pk_mul_f32 v[62:63], v[62:63], v[66:67]
	v_pk_mul_f32 v[58:59], v[58:59], v[70:71]
	v_pk_mul_f32 v[54:55], v[54:55], v[74:75]
	v_pk_mul_f32 v[64:65], v[64:65], v[68:69]
	v_pk_mul_f32 v[60:61], v[60:61], v[72:73]
	v_pk_mul_f32 v[56:57], v[56:57], v[76:77]
	v_pk_mul_f32 v[52:53], v[52:53], v[80:81]
	v_pk_mul_f32 v[50:51], v[50:51], v[78:79]
	v_pk_mul_f32 v[46:47], v[46:47], v[66:67]
	v_pk_mul_f32 v[42:43], v[42:43], v[70:71]
	v_pk_mul_f32 v[38:39], v[38:39], v[74:75]
	v_pk_mul_f32 v[48:49], v[48:49], v[68:69]
	v_pk_mul_f32 v[44:45], v[44:45], v[72:73]
	v_pk_mul_f32 v[40:41], v[40:41], v[76:77]
	v_pk_mul_f32 v[36:37], v[36:37], v[80:81]
	v_pk_mul_f32 v[34:35], v[34:35], v[78:79]
	v_pk_mul_f32 v[30:31], v[30:31], v[66:67]
	v_pk_mul_f32 v[26:27], v[26:27], v[70:71]
	v_pk_mul_f32 v[22:23], v[22:23], v[74:75]
	v_pk_mul_f32 v[32:33], v[32:33], v[68:69]
	v_pk_mul_f32 v[28:29], v[28:29], v[72:73]
	v_pk_mul_f32 v[24:25], v[24:25], v[76:77]
	v_pk_mul_f32 v[20:21], v[20:21], v[80:81]
	v_pk_mul_f32 v[18:19], v[18:19], v[78:79]
